# owner starts an L2 write-back before its last phase-B norm
# baseline (speedup 1.0000x reference)
; DI const bf16_t* wp(const Params& p, int l, size_t off) { return (const bf16_t*)(p.ws + OFF_WP) + (size_t)l * PW_LAYER + off; }
; template <int MT> DI void phaseB(const Params& p, int l, int t, unsigned char* lds) {
;     ...
;     gemm64<512, MT>(priv + PC_OX, PRIVW, d2, wp(p, l, PW_XO), DM / UW, lds, EpiResid<MT>{x, d2});
;     __syncthreads();
;     norm_rows<1, MT>(nullptr, nullptr, x, d2, xb, nullptr);
.LBB0_457:
	v_readfirstlane_b32 s100, v176
	s_nop 3
	s_cmp_lg_u32 s100, 0
	s_cbranch_scc1 .Lewb_u
	buffer_wbl2 sc1
